# pool/conv: 31 depthwise-conv tap weights loaded once before the unit loop (held in the former address registers) instead of per unit
# speedup vs baseline: 1.0070x; 1.0070x over previous
.LBB0_561:
	s_or_b64 exec, exec, s[12:13]
	s_add_u32 s12, s14, 0xbc00000
	s_addc_u32 s13, s15, 0
	s_and_b64 s[14:15], s[60:61], exec
	s_cselect_b32 s0, 0x7c00, 0
	s_add_u32 s30, s27, s0
	s_addc_u32 s31, s26, 0
	s_and_b64 s[14:15], s[60:61], exec
	s_cselect_b32 s0, 0x400, 0
	s_add_u32 s14, s21, s0
	s_addc_u32 s15, s3, 0
	s_add_u32 s20, s20, s0
	v_mov_b32_e32 v1, 2
	s_addc_u32 s21, s1, 0
	v_lshlrev_b32_sdwa v2, v1, v48 dst_sel:DWORD dst_unused:UNUSED_PAD src0_sel:DWORD src1_sel:BYTE_0
	v_lshlrev_b32_e32 v1, 4, v39
	global_load_dword v134, v2, s[14:15]
	global_load_dwordx4 v[20:23], v1, s[20:21]
	v_mov_b32_e32 v3, v0
	v_lshl_add_u64 v[46:47], s[30:31], 0, v[2:3]
	s_mov_b64 s[20:21], 0x1000
	v_ashrrev_i32_e32 v37, 8, v48
	v_lshlrev_b32_sdwa v44, v235, v48 dst_sel:DWORD dst_unused:UNUSED_PAD src0_sel:DWORD src1_sel:BYTE_0
	v_bfe_u32 v138, v48, 6, 2
	v_cmp_gt_u32_sdwa s[14:15], v48, v236 src0_sel:BYTE_0 src1_sel:DWORD
	v_lshl_add_u64 v[48:49], v[46:47], 0, s[20:21]
	s_mov_b64 s[20:21], 0x1400
	v_lshl_add_u64 v[50:51], v[46:47], 0, s[20:21]
	s_mov_b64 s[20:21], 0x1800
	v_lshl_add_u64 v[52:53], v[46:47], 0, s[20:21]
	s_mov_b64 s[20:21], 0x1c00
	v_lshl_add_u64 v[54:55], v[46:47], 0, s[20:21]
	s_mov_b64 s[20:21], 0x2000
	v_lshl_add_u64 v[56:57], v[46:47], 0, s[20:21]
	s_mov_b64 s[20:21], 0x2400
	v_lshl_add_u64 v[58:59], v[46:47], 0, s[20:21]
	s_mov_b64 s[20:21], 0x2800
	v_lshl_add_u64 v[60:61], v[46:47], 0, s[20:21]
	s_mov_b64 s[20:21], 0x2c00
	v_lshl_add_u64 v[62:63], v[46:47], 0, s[20:21]
	s_mov_b64 s[20:21], 0x3000
	v_lshl_add_u64 v[64:65], v[46:47], 0, s[20:21]
	s_mov_b64 s[20:21], 0x3400
	v_lshl_add_u64 v[66:67], v[46:47], 0, s[20:21]
	s_mov_b64 s[20:21], 0x3800
	v_lshl_add_u64 v[68:69], v[46:47], 0, s[20:21]
	s_mov_b64 s[20:21], 0x3c00
	v_lshl_add_u64 v[70:71], v[46:47], 0, s[20:21]
	s_mov_b64 s[20:21], 0x4000
	v_lshl_add_u64 v[72:73], v[46:47], 0, s[20:21]
	s_mov_b64 s[20:21], 0x4400
	v_lshl_add_u64 v[74:75], v[46:47], 0, s[20:21]
	s_mov_b64 s[20:21], 0x4800
	v_lshl_add_u64 v[76:77], v[46:47], 0, s[20:21]
	s_mov_b64 s[20:21], 0x4c00
	v_lshl_add_u64 v[78:79], v[46:47], 0, s[20:21]
	s_mov_b64 s[20:21], 0x5000
	v_lshl_add_u64 v[80:81], v[46:47], 0, s[20:21]
	s_mov_b64 s[20:21], 0x5400
	v_lshl_add_u64 v[82:83], v[46:47], 0, s[20:21]
	s_mov_b64 s[20:21], 0x5800
	v_lshl_add_u64 v[84:85], v[46:47], 0, s[20:21]
	s_mov_b64 s[20:21], 0x5c00
	v_lshlrev_b32_e32 v3, 14, v37
	s_add_i32 s0, 0, 0x10000
	v_lshl_add_u64 v[86:87], v[46:47], 0, s[20:21]
	s_mov_b64 s[20:21], 0x6000
	v_add_u32_e32 v107, s0, v3
	v_readlane_b32 s0, v255, 9
	v_lshl_add_u64 v[88:89], v[46:47], 0, s[20:21]
	s_mov_b64 s[20:21], 0x6400
	v_add_u32_e32 v108, s0, v3
	v_readlane_b32 s0, v255, 10
	v_lshl_add_u64 v[90:91], v[46:47], 0, s[20:21]
	s_mov_b64 s[20:21], 0x6800
	v_add_u32_e32 v109, s0, v3
	v_readlane_b32 s0, v255, 11
	v_lshl_add_u64 v[92:93], v[46:47], 0, s[20:21]
	s_mov_b64 s[20:21], 0x6c00
	v_add_u32_e32 v110, s0, v3
	v_readlane_b32 s0, v255, 12
	v_lshl_add_u64 v[94:95], v[46:47], 0, s[20:21]
	s_mov_b64 s[20:21], 0x7000
	v_add_u32_e32 v111, s0, v3
	v_readlane_b32 s0, v255, 13
	v_lshlrev_b32_e32 v136, 9, v130
	v_lshlrev_b32_e32 v38, 13, v37
	s_lshl_b32 s41, s35, 2
	v_lshl_add_u64 v[96:97], v[46:47], 0, s[20:21]
	s_mov_b64 s[20:21], 0x7400
	v_add_u32_e32 v112, s0, v3
	v_readlane_b32 s0, v255, 14
	v_add_u32_e32 v135, 0, v36
	v_add_u32_e32 v104, 0, v136
	v_add3_u32 v137, 0, v38, v44
	v_lshlrev_b32_e32 v139, 4, v37
	v_mov_b32_e32 v45, v0
	v_add_u32_e32 v140, 0, v1
	v_lshlrev_b32_e32 v1, 9, v131
	v_lshlrev_b32_e32 v105, 9, v132
	v_lshlrev_b32_e32 v106, 9, v133
	v_lshl_add_u64 v[98:99], v[46:47], 0, s[20:21]
	s_mov_b64 s[20:21], 0x7800
	v_add_u32_e32 v37, 0, v3
	v_add_u32_e32 v3, s0, v3
	s_or_b32 s44, s41, 1
	s_or_b32 s46, s41, 2
	s_or_b32 s57, s41, 3
	v_lshlrev_b32_e32 v38, 3, v39
	v_mov_b32_e32 v39, v0
	s_mov_b32 s40, 0
	v_lshl_add_u64 v[44:45], s[12:13], 0, v[44:45]
	v_lshl_add_u64 v[100:101], v[46:47], 0, s[20:21]
	s_lshl_b32 s35, s35, 12
	s_lshl_b32 s45, s44, 10
	s_lshl_b32 s56, s46, 10
	s_lshl_b32 s58, s57, 10
	v_lshl_add_u64 v[102:103], s[12:13], 0, v[38:39]
	v_add_u32_e32 v141, v135, v1
	v_add_u32_e32 v142, v135, v105
	v_add_u32_e32 v143, v135, v106
	v_add_u32_e32 v144, v104, v36
	v_add_u32_e32 v145, v37, v2
	v_add_u32_e32 v146, v107, v2
	v_add_u32_e32 v147, v108, v2
	v_add_u32_e32 v148, v109, v2
	v_add_u32_e32 v149, v110, v2
	v_add_u32_e32 v150, v111, v2
	v_add_u32_e32 v151, v112, v2
	v_add_u32_e32 v152, v3, v2
	global_load_dword v101, v[100:101], off
	global_load_dword v100, v[98:99], off
	global_load_dword v99, v[96:97], off
	global_load_dword v98, v[94:95], off
	global_load_dword v97, v[92:93], off
	global_load_dword v96, v[90:91], off
	global_load_dword v95, v[88:89], off
	global_load_dword v94, v[86:87], off
	global_load_dword v93, v[84:85], off
	global_load_dword v92, v[82:83], off
	global_load_dword v91, v[80:81], off
	global_load_dword v90, v[78:79], off
	global_load_dword v89, v[76:77], off
	global_load_dword v88, v[74:75], off
	global_load_dword v87, v[72:73], off
	global_load_dword v86, v[70:71], off
	global_load_dword v85, v[68:69], off
	global_load_dword v84, v[66:67], off
	global_load_dword v83, v[64:65], off
	global_load_dword v82, v[62:63], off
	global_load_dword v81, v[60:61], off
	global_load_dword v80, v[58:59], off
	global_load_dword v79, v[56:57], off
	global_load_dword v78, v[54:55], off
	global_load_dword v77, v[52:53], off
	global_load_dword v76, v[50:51], off
	global_load_dword v75, v[48:49], off
	global_load_dword v74, v[46:47], off offset:3072
	global_load_dword v73, v[46:47], off offset:2048
	global_load_dword v72, v[46:47], off offset:1024
	global_load_dword v71, v[46:47], off
	s_waitcnt vmcnt(0)
	s_branch .LBB0_563

.LBB0_591:
	ds_read_u16 v3, v137
	ds_read_u16 v37, v137 offset:512
	ds_read_u16 v107, v137 offset:1024
	ds_read_u16 v110, v137 offset:1536
	ds_read_u16 v114, v137 offset:2048
	ds_read_u16 v117, v137 offset:2560
	ds_read_u16 v120, v137 offset:3072
	ds_read_u16 v124, v137 offset:3584
	s_waitcnt lgkmcnt(7)
	v_lshlrev_b32_e32 v3, 16, v3
	s_waitcnt lgkmcnt(6)
	v_lshlrev_b32_e32 v37, 16, v37
	s_waitcnt lgkmcnt(5)
	v_lshlrev_b32_e32 v107, 16, v107
	s_waitcnt lgkmcnt(4)
	v_lshlrev_b32_e32 v110, 16, v110
	ds_read_u16 v128, v137 offset:4096
	ds_read_u16 v159, v137 offset:4608
	ds_read_u16 v161, v137 offset:5120
	ds_read_u16 v162, v137 offset:5632
	ds_read_u16 v163, v137 offset:6144
	ds_read_u16 v164, v137 offset:6656
	ds_read_u16 v165, v137 offset:7168
	ds_read_u16 v166, v137 offset:7680
	s_waitcnt lgkmcnt(11)
	v_lshlrev_b32_e32 v114, 16, v114
	s_waitcnt lgkmcnt(10)
	v_lshlrev_b32_e32 v117, 16, v117
	s_waitcnt lgkmcnt(9)
	v_lshlrev_b32_e32 v120, 16, v120
	s_waitcnt lgkmcnt(8)
	v_lshlrev_b32_e32 v124, 16, v124
	s_waitcnt lgkmcnt(7)
	v_lshlrev_b32_e32 v128, 16, v128
	s_waitcnt lgkmcnt(6)
	v_lshlrev_b32_e32 v159, 16, v159
	s_waitcnt lgkmcnt(5)
	v_lshlrev_b32_e32 v161, 16, v161
	s_waitcnt lgkmcnt(4)
	v_lshlrev_b32_e32 v162, 16, v162
	s_waitcnt lgkmcnt(3)
	v_lshlrev_b32_e32 v163, 16, v163
	s_waitcnt lgkmcnt(2)
	v_lshlrev_b32_e32 v164, 16, v164
	s_waitcnt lgkmcnt(1)
	v_lshlrev_b32_e32 v165, 16, v165
	s_waitcnt lgkmcnt(0)
	v_lshlrev_b32_e32 v166, 16, v166
	s_and_b32 s0, s59, 0xffffff00
	s_and_b32 s3, s59, 0x7ffff000
	s_add_i32 s12, s0, 0x100
	s_add_i32 s13, s3, 0x1000
	s_cmpk_lt_i32 s1, 0x100
	s_cselect_b32 s30, s0, s3
	s_cselect_b32 s31, s12, s13
	v_fma_f32 v3, v71, v3, v134
	v_fmac_f32_e32 v3, v72, v37
	v_fma_f32 v37, v71, v37, v134
	v_fmac_f32_e32 v3, v73, v107
	v_fmac_f32_e32 v37, v72, v107
	v_fma_f32 v107, v71, v107, v134
	v_fmac_f32_e32 v3, v74, v110
	v_fmac_f32_e32 v37, v73, v110
	v_fmac_f32_e32 v107, v72, v110
	v_fma_f32 v110, v71, v110, v134
	v_fmac_f32_e32 v3, v75, v114
	v_fmac_f32_e32 v37, v74, v114
	v_fmac_f32_e32 v107, v73, v114
	v_fmac_f32_e32 v110, v72, v114
	v_fma_f32 v114, v71, v114, v134
	v_fmac_f32_e32 v3, v76, v117
	v_fmac_f32_e32 v37, v75, v117
	v_fmac_f32_e32 v107, v74, v117
	v_fmac_f32_e32 v110, v73, v117
	v_fmac_f32_e32 v114, v72, v117
	v_fma_f32 v117, v71, v117, v134
	v_fmac_f32_e32 v3, v77, v120
	v_fmac_f32_e32 v37, v76, v120
	v_fmac_f32_e32 v107, v75, v120
	v_fmac_f32_e32 v110, v74, v120
	v_fmac_f32_e32 v114, v73, v120
	v_fmac_f32_e32 v117, v72, v120
	v_fma_f32 v120, v71, v120, v134
	v_fmac_f32_e32 v3, v78, v124
	v_fmac_f32_e32 v37, v77, v124
	v_fmac_f32_e32 v107, v76, v124
	v_fmac_f32_e32 v110, v75, v124
	v_fmac_f32_e32 v114, v74, v124
	v_fmac_f32_e32 v117, v73, v124
	v_fmac_f32_e32 v120, v72, v124
	v_fma_f32 v124, v71, v124, v134
	v_fmac_f32_e32 v3, v79, v128
	v_fmac_f32_e32 v37, v78, v128
	v_fmac_f32_e32 v107, v77, v128
	v_fmac_f32_e32 v110, v76, v128
	v_fmac_f32_e32 v114, v75, v128
	v_fmac_f32_e32 v117, v74, v128
	v_fmac_f32_e32 v120, v73, v128
	v_fmac_f32_e32 v124, v72, v128
	v_fma_f32 v128, v71, v128, v134
	v_fmac_f32_e32 v3, v80, v159
	v_fmac_f32_e32 v37, v79, v159
	v_fmac_f32_e32 v107, v78, v159
	v_fmac_f32_e32 v110, v77, v159
	v_fmac_f32_e32 v114, v76, v159
	v_fmac_f32_e32 v117, v75, v159
	v_fmac_f32_e32 v120, v74, v159
	v_fmac_f32_e32 v124, v73, v159
	v_fmac_f32_e32 v128, v72, v159
	v_fma_f32 v159, v71, v159, v134
	v_fmac_f32_e32 v3, v81, v161
	v_fmac_f32_e32 v37, v80, v161
	v_fmac_f32_e32 v107, v79, v161
	v_fmac_f32_e32 v110, v78, v161
	v_fmac_f32_e32 v114, v77, v161
	v_fmac_f32_e32 v117, v76, v161
	v_fmac_f32_e32 v120, v75, v161
	v_fmac_f32_e32 v124, v74, v161
	v_fmac_f32_e32 v128, v73, v161
	v_fmac_f32_e32 v159, v72, v161
	v_fma_f32 v161, v71, v161, v134
	v_fmac_f32_e32 v3, v82, v162
	v_fmac_f32_e32 v37, v81, v162
	v_fmac_f32_e32 v107, v80, v162
	v_fmac_f32_e32 v110, v79, v162
	v_fmac_f32_e32 v114, v78, v162
	v_fmac_f32_e32 v117, v77, v162
	v_fmac_f32_e32 v120, v76, v162
	v_fmac_f32_e32 v124, v75, v162
	v_fmac_f32_e32 v128, v74, v162
	v_fmac_f32_e32 v159, v73, v162
	v_fmac_f32_e32 v161, v72, v162
	v_fma_f32 v162, v71, v162, v134
	v_fmac_f32_e32 v3, v83, v163
	v_fmac_f32_e32 v37, v82, v163
	v_fmac_f32_e32 v107, v81, v163
	v_fmac_f32_e32 v110, v80, v163
	v_fmac_f32_e32 v114, v79, v163
	v_fmac_f32_e32 v117, v78, v163
	v_fmac_f32_e32 v120, v77, v163
	v_fmac_f32_e32 v124, v76, v163
	v_fmac_f32_e32 v128, v75, v163
	v_fmac_f32_e32 v159, v74, v163
	v_fmac_f32_e32 v161, v73, v163
	v_fmac_f32_e32 v162, v72, v163
	v_fma_f32 v163, v71, v163, v134
	v_fmac_f32_e32 v3, v84, v164
	v_fmac_f32_e32 v37, v83, v164
	v_fmac_f32_e32 v107, v82, v164
	v_fmac_f32_e32 v110, v81, v164
	v_fmac_f32_e32 v114, v80, v164
	v_fmac_f32_e32 v117, v79, v164
	v_fmac_f32_e32 v120, v78, v164
	v_fmac_f32_e32 v124, v77, v164
	v_fmac_f32_e32 v128, v76, v164
	v_fmac_f32_e32 v159, v75, v164
	v_fmac_f32_e32 v161, v74, v164
	v_fmac_f32_e32 v162, v73, v164
	v_fmac_f32_e32 v163, v72, v164
	v_fma_f32 v164, v71, v164, v134
	v_fmac_f32_e32 v3, v85, v165
	v_fmac_f32_e32 v37, v84, v165
	v_fmac_f32_e32 v107, v83, v165
	v_fmac_f32_e32 v110, v82, v165
	v_fmac_f32_e32 v114, v81, v165
	v_fmac_f32_e32 v117, v80, v165
	v_fmac_f32_e32 v120, v79, v165
	v_fmac_f32_e32 v124, v78, v165
	v_fmac_f32_e32 v128, v77, v165
	v_fmac_f32_e32 v159, v76, v165
	v_fmac_f32_e32 v161, v75, v165
	v_fmac_f32_e32 v162, v74, v165
	v_fmac_f32_e32 v163, v73, v165
	v_fmac_f32_e32 v164, v72, v165
	v_fma_f32 v165, v71, v165, v134
	v_fmac_f32_e32 v3, v86, v166
	v_fmac_f32_e32 v37, v85, v166
	v_fmac_f32_e32 v107, v84, v166
	v_fmac_f32_e32 v110, v83, v166
	v_fmac_f32_e32 v114, v82, v166
	v_fmac_f32_e32 v117, v81, v166
	v_fmac_f32_e32 v120, v80, v166
	v_fmac_f32_e32 v124, v79, v166
	v_fmac_f32_e32 v128, v78, v166
	v_fmac_f32_e32 v159, v77, v166
	v_fmac_f32_e32 v161, v76, v166
	v_fmac_f32_e32 v162, v75, v166
	v_fmac_f32_e32 v163, v74, v166
	v_fmac_f32_e32 v164, v73, v166
	v_fmac_f32_e32 v165, v72, v166
	v_fma_f32 v160, v71, v166, v134
	ds_read_u16 v166, v137 offset:8192
	s_waitcnt lgkmcnt(0)
	v_lshlrev_b32_e32 v166, 16, v166
	v_fmac_f32_e32 v160, v72, v166
	ds_read_u16 v158, v137 offset:8704
	v_fmac_f32_e32 v165, v73, v166
	v_fmac_f32_e32 v164, v74, v166
	v_fmac_f32_e32 v163, v75, v166
	v_fmac_f32_e32 v162, v76, v166
	s_waitcnt lgkmcnt(0)
	v_lshlrev_b32_e32 v158, 16, v158
	v_fmac_f32_e32 v160, v73, v158
	ds_read_u16 v157, v137 offset:9216
	v_fmac_f32_e32 v165, v74, v158
	v_fmac_f32_e32 v164, v75, v158
	v_fmac_f32_e32 v163, v76, v158
	v_fmac_f32_e32 v161, v77, v166
	s_waitcnt lgkmcnt(0)
	v_lshlrev_b32_e32 v157, 16, v157
	v_fmac_f32_e32 v160, v74, v157
	ds_read_u16 v156, v137 offset:9728
	v_fmac_f32_e32 v165, v75, v157
	v_fmac_f32_e32 v164, v76, v157
	v_fmac_f32_e32 v162, v77, v158
	v_fmac_f32_e32 v163, v77, v157
	s_waitcnt lgkmcnt(0)
	v_lshlrev_b32_e32 v156, 16, v156
	v_fmac_f32_e32 v160, v75, v156
	ds_read_u16 v155, v137 offset:10240
	v_fmac_f32_e32 v165, v76, v156
	v_fmac_f32_e32 v164, v77, v156
	v_fmac_f32_e32 v159, v78, v166
	v_fmac_f32_e32 v161, v78, v158
	s_waitcnt lgkmcnt(0)
	v_lshlrev_b32_e32 v155, 16, v155
	v_fmac_f32_e32 v160, v76, v155
	ds_read_u16 v154, v137 offset:10752
	v_fmac_f32_e32 v165, v77, v155
	v_fmac_f32_e32 v162, v78, v157
	v_fmac_f32_e32 v163, v78, v156
	v_fmac_f32_e32 v164, v78, v155
	s_waitcnt lgkmcnt(0)
	v_lshlrev_b32_e32 v154, 16, v154
	v_fmac_f32_e32 v160, v77, v154
	ds_read_u16 v153, v137 offset:11264
	v_fmac_f32_e32 v165, v78, v154
	v_fmac_f32_e32 v128, v79, v166
	v_fmac_f32_e32 v159, v79, v158
	v_fmac_f32_e32 v161, v79, v157
	s_waitcnt lgkmcnt(0)
	v_lshlrev_b32_e32 v153, 16, v153
	v_fmac_f32_e32 v160, v78, v153
	ds_read_u16 v129, v137 offset:11776
	v_fmac_f32_e32 v162, v79, v156
	v_fmac_f32_e32 v163, v79, v155
	v_fmac_f32_e32 v164, v79, v154
	v_fmac_f32_e32 v165, v79, v153
	s_waitcnt lgkmcnt(0)
	v_lshlrev_b32_e32 v129, 16, v129
	v_fmac_f32_e32 v160, v79, v129
	ds_read_u16 v127, v137 offset:12288
	v_fmac_f32_e32 v124, v80, v166
	v_fmac_f32_e32 v128, v80, v158
	v_fmac_f32_e32 v159, v80, v157
	v_fmac_f32_e32 v161, v80, v156
	s_waitcnt lgkmcnt(0)
	v_lshlrev_b32_e32 v127, 16, v127
	v_fmac_f32_e32 v162, v80, v155
	v_fmac_f32_e32 v163, v80, v154
	v_fmac_f32_e32 v164, v80, v153
	v_fmac_f32_e32 v165, v80, v129
	v_fmac_f32_e32 v160, v80, v127
	ds_read_u16 v126, v137 offset:12800
	v_fmac_f32_e32 v120, v81, v166
	v_fmac_f32_e32 v124, v81, v158
	v_fmac_f32_e32 v128, v81, v157
	v_fmac_f32_e32 v159, v81, v156
	s_waitcnt lgkmcnt(0)
	v_lshlrev_b32_e32 v126, 16, v126
	v_fmac_f32_e32 v161, v81, v155
	v_fmac_f32_e32 v162, v81, v154
	v_fmac_f32_e32 v163, v81, v153
	v_fmac_f32_e32 v164, v81, v129
	v_fmac_f32_e32 v165, v81, v127
	v_fmac_f32_e32 v160, v81, v126
	ds_read_u16 v125, v137 offset:13312
	v_fmac_f32_e32 v117, v82, v166
	v_fmac_f32_e32 v120, v82, v158
	v_fmac_f32_e32 v124, v82, v157
	v_fmac_f32_e32 v128, v82, v156
	s_waitcnt lgkmcnt(0)
	v_lshlrev_b32_e32 v125, 16, v125
	v_fmac_f32_e32 v159, v82, v155
	v_fmac_f32_e32 v161, v82, v154
	v_fmac_f32_e32 v162, v82, v153
	v_fmac_f32_e32 v163, v82, v129
	v_fmac_f32_e32 v164, v82, v127
	v_fmac_f32_e32 v165, v82, v126
	v_fmac_f32_e32 v160, v82, v125
	ds_read_u16 v123, v137 offset:13824
	v_fmac_f32_e32 v114, v83, v166
	v_fmac_f32_e32 v117, v83, v158
	v_fmac_f32_e32 v120, v83, v157
	v_fmac_f32_e32 v124, v83, v156
	s_waitcnt lgkmcnt(0)
	v_lshlrev_b32_e32 v123, 16, v123
	v_fmac_f32_e32 v128, v83, v155
	v_fmac_f32_e32 v159, v83, v154
	v_fmac_f32_e32 v161, v83, v153
	v_fmac_f32_e32 v162, v83, v129
	v_fmac_f32_e32 v163, v83, v127
	v_fmac_f32_e32 v164, v83, v126
	v_fmac_f32_e32 v165, v83, v125
	v_fmac_f32_e32 v160, v83, v123
	ds_read_u16 v122, v137 offset:14336
	v_fmac_f32_e32 v110, v84, v166
	v_fmac_f32_e32 v114, v84, v158
	v_fmac_f32_e32 v117, v84, v157
	v_fmac_f32_e32 v120, v84, v156
	s_waitcnt lgkmcnt(0)
	v_lshlrev_b32_e32 v122, 16, v122
	v_fmac_f32_e32 v124, v84, v155
	v_fmac_f32_e32 v128, v84, v154
	v_fmac_f32_e32 v159, v84, v153
	v_fmac_f32_e32 v161, v84, v129
	v_fmac_f32_e32 v162, v84, v127
	v_fmac_f32_e32 v163, v84, v126
	v_fmac_f32_e32 v164, v84, v125
	v_fmac_f32_e32 v165, v84, v123
	v_fmac_f32_e32 v160, v84, v122
	ds_read_u16 v121, v137 offset:14848
	v_fmac_f32_e32 v107, v85, v166
	v_fmac_f32_e32 v110, v85, v158
	v_fmac_f32_e32 v114, v85, v157
	v_fmac_f32_e32 v117, v85, v156
	s_waitcnt lgkmcnt(0)
	v_lshlrev_b32_e32 v121, 16, v121
	v_fmac_f32_e32 v120, v85, v155
	v_fmac_f32_e32 v124, v85, v154
	v_fmac_f32_e32 v128, v85, v153
	v_fmac_f32_e32 v159, v85, v129
	v_fmac_f32_e32 v161, v85, v127
	v_fmac_f32_e32 v162, v85, v126
	v_fmac_f32_e32 v163, v85, v125
	v_fmac_f32_e32 v164, v85, v123
	v_fmac_f32_e32 v165, v85, v122
	v_fmac_f32_e32 v160, v85, v121
	ds_read_u16 v119, v137 offset:15360
	v_fmac_f32_e32 v37, v86, v166
	v_fmac_f32_e32 v107, v86, v158
	v_fmac_f32_e32 v110, v86, v157
	v_fmac_f32_e32 v114, v86, v156
	s_waitcnt lgkmcnt(0)
	v_lshlrev_b32_e32 v119, 16, v119
	v_fmac_f32_e32 v117, v86, v155
	v_fmac_f32_e32 v120, v86, v154
	v_fmac_f32_e32 v124, v86, v153
	v_fmac_f32_e32 v128, v86, v129
	v_fmac_f32_e32 v159, v86, v127
	v_fmac_f32_e32 v161, v86, v126
	v_fmac_f32_e32 v162, v86, v125
	v_fmac_f32_e32 v163, v86, v123
	v_fmac_f32_e32 v164, v86, v122
	v_fmac_f32_e32 v165, v86, v121
	v_fmac_f32_e32 v160, v86, v119
	ds_read_u16 v118, v137 offset:15872
	v_fmac_f32_e32 v3, v87, v166
	v_fmac_f32_e32 v37, v87, v158
	v_fmac_f32_e32 v107, v87, v157
	v_fmac_f32_e32 v110, v87, v156
	s_waitcnt lgkmcnt(0)
	v_lshlrev_b32_e32 v118, 16, v118
	v_fmac_f32_e32 v114, v87, v155
	v_fmac_f32_e32 v117, v87, v154
	v_fmac_f32_e32 v120, v87, v153
	v_fmac_f32_e32 v124, v87, v129
	v_fmac_f32_e32 v128, v87, v127
	v_fmac_f32_e32 v159, v87, v126
	v_fmac_f32_e32 v161, v87, v125
	v_fmac_f32_e32 v162, v87, v123
	v_fmac_f32_e32 v163, v87, v122
	v_fmac_f32_e32 v164, v87, v121
	v_fmac_f32_e32 v165, v87, v119
	v_fmac_f32_e32 v160, v87, v118
	ds_read_u16 v116, v137 offset:16384
	v_fmac_f32_e32 v3, v88, v158
	v_fmac_f32_e32 v37, v88, v157
	v_fmac_f32_e32 v107, v88, v156
	v_fmac_f32_e32 v110, v88, v155
	s_waitcnt lgkmcnt(0)
	v_lshlrev_b32_e32 v116, 16, v116
	v_fmac_f32_e32 v114, v88, v154
	v_fmac_f32_e32 v117, v88, v153
	v_fmac_f32_e32 v120, v88, v129
	v_fmac_f32_e32 v124, v88, v127
	v_fmac_f32_e32 v128, v88, v126
	v_fmac_f32_e32 v159, v88, v125
	v_fmac_f32_e32 v161, v88, v123
	v_fmac_f32_e32 v162, v88, v122
	v_fmac_f32_e32 v163, v88, v121
	v_fmac_f32_e32 v164, v88, v119
	v_fmac_f32_e32 v165, v88, v118
	v_fmac_f32_e32 v160, v88, v116
	ds_read_u16 v115, v137 offset:16896
	v_fmac_f32_e32 v3, v89, v157
	v_fmac_f32_e32 v37, v89, v156
	v_fmac_f32_e32 v107, v89, v155
	v_fmac_f32_e32 v110, v89, v154
	s_waitcnt lgkmcnt(0)
	v_lshlrev_b32_e32 v115, 16, v115
	v_fmac_f32_e32 v114, v89, v153
	v_fmac_f32_e32 v117, v89, v129
	v_fmac_f32_e32 v120, v89, v127
	v_fmac_f32_e32 v124, v89, v126
	v_fmac_f32_e32 v128, v89, v125
	v_fmac_f32_e32 v159, v89, v123
	v_fmac_f32_e32 v161, v89, v122
	v_fmac_f32_e32 v162, v89, v121
	v_fmac_f32_e32 v163, v89, v119
	v_fmac_f32_e32 v164, v89, v118
	v_fmac_f32_e32 v165, v89, v116
	v_fmac_f32_e32 v160, v89, v115
	ds_read_u16 v113, v137 offset:17408
	v_fmac_f32_e32 v3, v90, v156
	v_fmac_f32_e32 v37, v90, v155
	v_fmac_f32_e32 v107, v90, v154
	v_fmac_f32_e32 v110, v90, v153
	s_waitcnt lgkmcnt(0)
	v_lshlrev_b32_e32 v113, 16, v113
	v_fmac_f32_e32 v114, v90, v129
	v_fmac_f32_e32 v117, v90, v127
	v_fmac_f32_e32 v120, v90, v126
	v_fmac_f32_e32 v124, v90, v125
	v_fmac_f32_e32 v128, v90, v123
	v_fmac_f32_e32 v159, v90, v122
	v_fmac_f32_e32 v161, v90, v121
	v_fmac_f32_e32 v162, v90, v119
	v_fmac_f32_e32 v163, v90, v118
	v_fmac_f32_e32 v164, v90, v116
	v_fmac_f32_e32 v165, v90, v115
	v_fmac_f32_e32 v160, v90, v113
	ds_read_u16 v112, v137 offset:17920
	v_fmac_f32_e32 v3, v91, v155
	v_fmac_f32_e32 v37, v91, v154
	v_fmac_f32_e32 v107, v91, v153
	v_fmac_f32_e32 v110, v91, v129
	s_waitcnt lgkmcnt(0)
	v_lshlrev_b32_e32 v112, 16, v112
	v_fmac_f32_e32 v114, v91, v127
	v_fmac_f32_e32 v117, v91, v126
	v_fmac_f32_e32 v120, v91, v125
	v_fmac_f32_e32 v124, v91, v123
	v_fmac_f32_e32 v128, v91, v122
	v_fmac_f32_e32 v159, v91, v121
	v_fmac_f32_e32 v161, v91, v119
	v_fmac_f32_e32 v162, v91, v118
	v_fmac_f32_e32 v163, v91, v116
	v_fmac_f32_e32 v164, v91, v115
	v_fmac_f32_e32 v165, v91, v113
	v_fmac_f32_e32 v160, v91, v112
	ds_read_u16 v111, v137 offset:18432
	v_fmac_f32_e32 v3, v92, v154
	v_fmac_f32_e32 v37, v92, v153
	v_fmac_f32_e32 v107, v92, v129
	v_fmac_f32_e32 v110, v92, v127
	s_waitcnt lgkmcnt(0)
	v_lshlrev_b32_e32 v111, 16, v111
	v_fmac_f32_e32 v114, v92, v126
	v_fmac_f32_e32 v117, v92, v125
	v_fmac_f32_e32 v120, v92, v123
	v_fmac_f32_e32 v124, v92, v122
	v_fmac_f32_e32 v128, v92, v121
	v_fmac_f32_e32 v159, v92, v119
	v_fmac_f32_e32 v161, v92, v118
	v_fmac_f32_e32 v162, v92, v116
	v_fmac_f32_e32 v163, v92, v115
	v_fmac_f32_e32 v164, v92, v113
	v_fmac_f32_e32 v165, v92, v112
	v_fmac_f32_e32 v160, v92, v111
	ds_read_u16 v109, v137 offset:18944
	v_fmac_f32_e32 v3, v93, v153
	v_fmac_f32_e32 v37, v93, v129
	v_fmac_f32_e32 v107, v93, v127
	v_fmac_f32_e32 v110, v93, v126
	s_waitcnt lgkmcnt(0)
	v_lshlrev_b32_e32 v109, 16, v109
	v_fmac_f32_e32 v114, v93, v125
	v_fmac_f32_e32 v117, v93, v123
	v_fmac_f32_e32 v120, v93, v122
	v_fmac_f32_e32 v124, v93, v121
	v_fmac_f32_e32 v128, v93, v119
	v_fmac_f32_e32 v159, v93, v118
	v_fmac_f32_e32 v161, v93, v116
	v_fmac_f32_e32 v162, v93, v115
	v_fmac_f32_e32 v163, v93, v113
	v_fmac_f32_e32 v164, v93, v112
	v_fmac_f32_e32 v165, v93, v111
	v_fmac_f32_e32 v160, v93, v109
	ds_read_u16 v108, v137 offset:19456
	v_fmac_f32_e32 v3, v94, v129
	v_fmac_f32_e32 v37, v94, v127
	v_fmac_f32_e32 v107, v94, v126
	v_fmac_f32_e32 v110, v94, v125
	s_waitcnt lgkmcnt(0)
	v_lshlrev_b32_e32 v108, 16, v108
	v_fmac_f32_e32 v114, v94, v123
	v_fmac_f32_e32 v117, v94, v122
	v_fmac_f32_e32 v120, v94, v121
	v_fmac_f32_e32 v124, v94, v119
	v_fmac_f32_e32 v128, v94, v118
	v_fmac_f32_e32 v159, v94, v116
	v_fmac_f32_e32 v161, v94, v115
	v_fmac_f32_e32 v162, v94, v113
	v_fmac_f32_e32 v163, v94, v112
	v_fmac_f32_e32 v164, v94, v111
	v_fmac_f32_e32 v165, v94, v109
	v_fmac_f32_e32 v160, v94, v108
	ds_read_u16 v106, v137 offset:19968
	v_fmac_f32_e32 v3, v95, v127
	v_fmac_f32_e32 v37, v95, v126
	v_fmac_f32_e32 v107, v95, v125
	v_fmac_f32_e32 v110, v95, v123
	s_waitcnt lgkmcnt(0)
	v_lshlrev_b32_e32 v106, 16, v106
	v_fmac_f32_e32 v114, v95, v122
	v_fmac_f32_e32 v117, v95, v121
	v_fmac_f32_e32 v120, v95, v119
	v_fmac_f32_e32 v124, v95, v118
	v_fmac_f32_e32 v128, v95, v116
	v_fmac_f32_e32 v159, v95, v115
	v_fmac_f32_e32 v161, v95, v113
	v_fmac_f32_e32 v162, v95, v112
	v_fmac_f32_e32 v163, v95, v111
	v_fmac_f32_e32 v164, v95, v109
	v_fmac_f32_e32 v165, v95, v108
	v_fmac_f32_e32 v160, v95, v106
	ds_read_u16 v105, v137 offset:20480
	v_fmac_f32_e32 v3, v96, v126
	v_fmac_f32_e32 v37, v96, v125
	v_fmac_f32_e32 v107, v96, v123
	v_fmac_f32_e32 v110, v96, v122
	s_waitcnt lgkmcnt(0)
	v_lshlrev_b32_e32 v105, 16, v105
	v_fmac_f32_e32 v114, v96, v121
	v_fmac_f32_e32 v117, v96, v119
	v_fmac_f32_e32 v120, v96, v118
	v_fmac_f32_e32 v124, v96, v116
	v_fmac_f32_e32 v128, v96, v115
	v_fmac_f32_e32 v159, v96, v113
	v_fmac_f32_e32 v161, v96, v112
	v_fmac_f32_e32 v162, v96, v111
	v_fmac_f32_e32 v163, v96, v109
	v_fmac_f32_e32 v164, v96, v108
	v_fmac_f32_e32 v165, v96, v106
	v_fmac_f32_e32 v160, v96, v105
	ds_read_u16 v104, v137 offset:20992
	v_fmac_f32_e32 v3, v97, v125
	v_fmac_f32_e32 v37, v97, v123
	v_fmac_f32_e32 v107, v97, v122
	v_fmac_f32_e32 v110, v97, v121
	s_waitcnt lgkmcnt(0)
	v_lshlrev_b32_e32 v104, 16, v104
	v_fmac_f32_e32 v114, v97, v119
	v_fmac_f32_e32 v117, v97, v118
	v_fmac_f32_e32 v120, v97, v116
	v_fmac_f32_e32 v124, v97, v115
	v_fmac_f32_e32 v128, v97, v113
	v_fmac_f32_e32 v159, v97, v112
	v_fmac_f32_e32 v161, v97, v111
	v_fmac_f32_e32 v162, v97, v109
	v_fmac_f32_e32 v163, v97, v108
	v_fmac_f32_e32 v164, v97, v106
	v_fmac_f32_e32 v165, v97, v105
	v_fmac_f32_e32 v160, v97, v104
	ds_read_u16 v39, v137 offset:21504
	v_fmac_f32_e32 v3, v98, v123
	v_fmac_f32_e32 v37, v98, v122
	v_fmac_f32_e32 v107, v98, v121
	v_fmac_f32_e32 v110, v98, v119
	s_waitcnt lgkmcnt(0)
	v_lshlrev_b32_e32 v39, 16, v39
	v_fmac_f32_e32 v114, v98, v118
	v_fmac_f32_e32 v117, v98, v116
	v_fmac_f32_e32 v120, v98, v115
	v_fmac_f32_e32 v124, v98, v113
	v_fmac_f32_e32 v128, v98, v112
	v_fmac_f32_e32 v159, v98, v111
	v_fmac_f32_e32 v161, v98, v109
	v_fmac_f32_e32 v162, v98, v108
	v_fmac_f32_e32 v163, v98, v106
	v_fmac_f32_e32 v164, v98, v105
	v_fmac_f32_e32 v165, v98, v104
	v_fmac_f32_e32 v160, v98, v39
	ds_read_u16 v38, v137 offset:22016
	v_fmac_f32_e32 v3, v99, v122
	v_fmac_f32_e32 v37, v99, v121
	v_fmac_f32_e32 v107, v99, v119
	v_fmac_f32_e32 v110, v99, v118
	s_waitcnt lgkmcnt(0)
	v_lshlrev_b32_e32 v38, 16, v38
	v_fmac_f32_e32 v114, v99, v116
	v_fmac_f32_e32 v117, v99, v115
	v_fmac_f32_e32 v120, v99, v113
	v_fmac_f32_e32 v124, v99, v112
	v_fmac_f32_e32 v128, v99, v111
	v_fmac_f32_e32 v159, v99, v109
	v_fmac_f32_e32 v161, v99, v108
	v_fmac_f32_e32 v162, v99, v106
	v_fmac_f32_e32 v163, v99, v105
	v_fmac_f32_e32 v164, v99, v104
	v_fmac_f32_e32 v165, v99, v39
	v_fmac_f32_e32 v160, v99, v38
	ds_read_u16 v36, v137 offset:22528
	v_fmac_f32_e32 v3, v100, v121
	v_fmac_f32_e32 v37, v100, v119
	v_fmac_f32_e32 v107, v100, v118
	v_fmac_f32_e32 v110, v100, v116
	s_waitcnt lgkmcnt(0)
	v_lshlrev_b32_e32 v36, 16, v36
	v_fmac_f32_e32 v114, v100, v115
	v_fmac_f32_e32 v117, v100, v113
	v_fmac_f32_e32 v120, v100, v112
	v_fmac_f32_e32 v124, v100, v111
	v_fmac_f32_e32 v128, v100, v109
	v_fmac_f32_e32 v159, v100, v108
	v_fmac_f32_e32 v161, v100, v106
	v_fmac_f32_e32 v162, v100, v105
	v_fmac_f32_e32 v163, v100, v104
	v_fmac_f32_e32 v164, v100, v39
	v_fmac_f32_e32 v165, v100, v38
	v_fmac_f32_e32 v160, v100, v36
	ds_read_u16 v2, v137 offset:23040
	v_fmac_f32_e32 v3, v101, v119
	v_fmac_f32_e32 v37, v101, v118
	v_fmac_f32_e32 v107, v101, v116
	v_fmac_f32_e32 v110, v101, v115
	s_waitcnt lgkmcnt(0)
	v_lshlrev_b32_e32 v2, 16, v2
	v_fmac_f32_e32 v114, v101, v113
	v_fmac_f32_e32 v117, v101, v112
	v_fmac_f32_e32 v120, v101, v111
	v_fmac_f32_e32 v124, v101, v109
	v_fmac_f32_e32 v128, v101, v108
	v_fmac_f32_e32 v159, v101, v106
	v_fmac_f32_e32 v161, v101, v105
	v_fmac_f32_e32 v162, v101, v104
	v_fmac_f32_e32 v163, v101, v39
	v_fmac_f32_e32 v164, v101, v38
	v_fmac_f32_e32 v165, v101, v36
	v_fmac_f32_e32 v160, v101, v2
	ds_write2st64_b32 v145, v3, v37 offset0:220 offset1:224
	ds_write2st64_b32 v145, v107, v110 offset0:228 offset1:232
	ds_write2st64_b32 v145, v114, v117 offset0:236 offset1:240
	ds_write2st64_b32 v145, v120, v124 offset0:244 offset1:248
	ds_write_b32 v145, v128 offset:64512
	ds_write_b32 v146, v159
	ds_write_b32 v147, v161
	ds_write_b32 v148, v162
	ds_write_b32 v149, v163
	ds_write_b32 v150, v164
	ds_write_b32 v151, v165
	ds_write_b32 v152, v160
	ds_read_u16 v1, v137 offset:31744
	ds_read_u16 v2, v137 offset:40960
	s_waitcnt lgkmcnt(1)
	v_lshlrev_b32_e32 v1, 16, v1
	v_add_f32_e32 v122, 0, v1
	ds_read_u16 v1, v137 offset:32256
	s_waitcnt lgkmcnt(1)
	v_lshlrev_b32_e32 v2, 16, v2
	s_waitcnt lgkmcnt(0)
	v_lshlrev_b32_e32 v1, 16, v1
	v_add_f32_e32 v120, v122, v1
	ds_read_u16 v1, v137 offset:32768
	s_waitcnt lgkmcnt(0)
	v_lshlrev_b32_e32 v1, 16, v1
	v_add_f32_e32 v121, v120, v1
	ds_read_u16 v1, v137 offset:33280
	s_waitcnt lgkmcnt(0)
	v_lshlrev_b32_e32 v1, 16, v1
	v_add_f32_e32 v123, v121, v1
	ds_read_u16 v1, v137 offset:33792
	s_waitcnt lgkmcnt(0)
	v_lshlrev_b32_e32 v1, 16, v1
	v_add_f32_e32 v125, v123, v1
	ds_read_u16 v1, v137 offset:34304
	s_waitcnt lgkmcnt(0)
	v_lshlrev_b32_e32 v1, 16, v1
	v_add_f32_e32 v164, v125, v1
	ds_read_u16 v1, v137 offset:34816
	s_waitcnt lgkmcnt(0)
	v_lshlrev_b32_e32 v1, 16, v1
	v_add_f32_e32 v163, v164, v1
	ds_read_u16 v1, v137 offset:35328
	s_waitcnt lgkmcnt(0)
	v_lshlrev_b32_e32 v1, 16, v1
	v_add_f32_e32 v162, v163, v1
	ds_read_u16 v1, v137 offset:35840
	s_waitcnt lgkmcnt(0)
	v_lshlrev_b32_e32 v1, 16, v1
	v_add_f32_e32 v161, v162, v1
	ds_read_u16 v1, v137 offset:36352
	s_waitcnt lgkmcnt(0)
	v_lshlrev_b32_e32 v1, 16, v1
	v_add_f32_e32 v160, v161, v1
	ds_read_u16 v1, v137 offset:36864
	s_waitcnt lgkmcnt(0)
	v_lshlrev_b32_e32 v1, 16, v1
	v_add_f32_e32 v159, v160, v1
	ds_read_u16 v1, v137 offset:37376
	s_waitcnt lgkmcnt(0)
	v_lshlrev_b32_e32 v1, 16, v1
	v_add_f32_e32 v158, v159, v1
	ds_read_u16 v1, v137 offset:37888
	s_waitcnt lgkmcnt(0)
	v_lshlrev_b32_e32 v1, 16, v1
	v_add_f32_e32 v157, v158, v1
	ds_read_u16 v1, v137 offset:38400
	s_waitcnt lgkmcnt(0)
	v_lshlrev_b32_e32 v1, 16, v1
	v_add_f32_e32 v156, v157, v1
	ds_read_u16 v1, v137 offset:38912
	s_waitcnt lgkmcnt(0)
	v_lshlrev_b32_e32 v1, 16, v1
	v_add_f32_e32 v155, v156, v1
	ds_read_u16 v1, v137 offset:39424
	s_waitcnt lgkmcnt(0)
	v_lshlrev_b32_e32 v1, 16, v1
	v_add_f32_e32 v154, v155, v1
	ds_read_u16 v1, v137 offset:39936
	s_waitcnt lgkmcnt(0)
	v_lshlrev_b32_e32 v1, 16, v1
	v_add_f32_e32 v153, v154, v1
	ds_read_u16 v1, v137 offset:40448
	s_waitcnt lgkmcnt(0)
	v_lshlrev_b32_e32 v1, 16, v1
	v_add_f32_e32 v1, v153, v1
	v_add_f32_e32 v169, v1, v2
	ds_read_u16 v2, v137 offset:41472
	s_waitcnt lgkmcnt(0)
	v_lshlrev_b32_e32 v2, 16, v2
	v_add_f32_e32 v168, v169, v2
	ds_read_u16 v2, v137 offset:41984
	s_waitcnt lgkmcnt(0)
	v_lshlrev_b32_e32 v2, 16, v2
	v_add_f32_e32 v166, v168, v2
	ds_read_u16 v2, v137 offset:42496
	s_waitcnt lgkmcnt(0)
	v_lshlrev_b32_e32 v2, 16, v2
	v_add_f32_e32 v167, v166, v2
	ds_read_u16 v2, v137 offset:43008
	s_waitcnt lgkmcnt(0)
	v_lshlrev_b32_e32 v2, 16, v2
	v_add_f32_e32 v165, v167, v2
	ds_read_u16 v2, v137 offset:43520
	s_waitcnt lgkmcnt(0)
	v_lshlrev_b32_e32 v2, 16, v2
	v_add_f32_e32 v170, v165, v2
	v_add_u32_e32 v2, s59, v139
	s_and_saveexec_b64 s[12:13], s[14:15]
	s_xor_b64 s[12:13], exec, s[12:13]
	s_cbranch_execz .LBB0_603
	ds_read_u16 v127, v137 offset:45568
	ds_read_u16 v124, v137 offset:46080
	ds_read_u16 v3, v137 offset:44032
	ds_read_u16 v126, v137 offset:46592
	ds_read_u16 v36, v137 offset:44544
	ds_read_u16 v128, v137 offset:47104
	ds_read_u16 v37, v137 offset:45056
	s_waitcnt lgkmcnt(4)
	v_lshlrev_b32_e32 v3, 16, v3
	v_add_f32_e32 v171, v170, v3
	s_waitcnt lgkmcnt(2)
	v_lshlrev_b32_e32 v3, 16, v36
	v_add_f32_e32 v175, v171, v3
	s_waitcnt lgkmcnt(0)
	v_lshlrev_b32_e32 v3, 16, v37
	v_sub_f32_e32 v172, v161, v162
	v_add_f32_e32 v174, v175, v3
	v_cmp_lt_i32_e32 vcc, 1, v138
	s_mov_b64 s[42:43], 0
	s_mov_b64 s[26:27], 0
	s_and_saveexec_b64 s[20:21], vcc
	s_xor_b64 s[50:51], exec, s[20:21]
	s_cbranch_execz .LBB0_596
	v_cmp_eq_u32_e32 vcc, 2, v138
	s_mov_b64 s[20:21], -1
	s_and_saveexec_b64 s[52:53], vcc
	s_cbranch_execz .LBB0_595
	v_add_u32_e32 v3, -4, v2
	v_or_b32_e32 v112, 4, v2
	v_max_i32_e32 v3, s30, v3
	v_min_i32_e32 v36, s31, v112
	v_sub_u32_e32 v3, v36, v3
	v_cvt_f32_i32_e32 v3, v3
	v_sub_f32_e32 v37, v158, v123
	v_or_b32_e32 v110, 1, v2
	v_sub_f32_e32 v39, v157, v125
	v_rcp_iflag_f32_e32 v3, v3
	v_ashrrev_i32_e32 v111, 31, v110
	v_or_b32_e32 v114, 2, v2
	v_sub_f32_e32 v104, v156, v164
	v_fma_f32 v3, v3, v37, -v172
	v_cvt_pk_bf16_f32 v38, v3, s0
	v_ashrrev_i32_e32 v3, 31, v2
	v_lshlrev_b64 v[36:37], 11, v[2:3]
	v_lshl_add_u64 v[36:37], v[44:45], 0, v[36:37]
	global_store_short v[36:37], v38, off
	v_add_u32_e32 v3, -3, v2
	v_or_b32_e32 v36, 5, v2
	v_max_i32_e32 v3, s30, v3
	v_min_i32_e32 v37, s31, v36
	v_sub_u32_e32 v3, v37, v3
	v_cvt_f32_i32_e32 v3, v3
	v_sub_f32_e32 v38, v160, v161
	v_ashrrev_i32_e32 v115, 31, v114
	v_or_b32_e32 v116, 3, v2
	v_rcp_iflag_f32_e32 v3, v3
	v_ashrrev_i32_e32 v117, 31, v116
	v_lshlrev_b64 v[106:107], 11, v[116:117]
	v_lshl_add_u64 v[106:107], v[44:45], 0, v[106:107]
	v_fma_f32 v3, v3, v39, -v38
	v_lshlrev_b64 v[38:39], 11, v[110:111]
	v_cvt_pk_bf16_f32 v3, v3, s0
	v_lshl_add_u64 v[38:39], v[44:45], 0, v[38:39]
	global_store_short v[38:39], v3, off
	v_add_u32_e32 v3, -2, v2
	v_or_b32_e32 v38, 6, v2
	v_max_i32_e32 v3, s30, v3
	v_min_i32_e32 v37, s31, v38
	v_sub_u32_e32 v3, v37, v3
	v_cvt_f32_i32_e32 v3, v3
	v_sub_f32_e32 v39, v159, v160
	v_ashrrev_i32_e32 v113, 31, v112
	v_lshlrev_b64 v[108:109], 11, v[112:113]
	v_rcp_iflag_f32_e32 v3, v3
	v_lshl_add_u64 v[108:109], v[44:45], 0, v[108:109]
	v_or_b32_e32 v118, 13, v2
	v_ashrrev_i32_e32 v119, 31, v118
	v_fma_f32 v3, v3, v104, -v39
	v_lshlrev_b64 v[104:105], 11, v[114:115]
	v_cvt_pk_bf16_f32 v3, v3, s0
	v_lshl_add_u64 v[104:105], v[44:45], 0, v[104:105]
	global_store_short v[104:105], v3, off
	v_add_u32_e32 v3, -1, v2
	v_or_b32_e32 v104, 7, v2
	v_max_i32_e32 v3, s30, v3
	v_min_i32_e32 v37, s31, v104
	v_sub_u32_e32 v3, v37, v3
	v_cvt_f32_i32_e32 v3, v3
	v_sub_f32_e32 v39, v158, v159
	v_sub_f32_e32 v105, v155, v163
	s_xor_b64 s[20:21], exec, -1
	v_rcp_iflag_f32_e32 v3, v3
	s_nop 0
	v_fma_f32 v3, v3, v105, -v39
	v_cvt_pk_bf16_f32 v3, v3, s0
	global_store_short v[106:107], v3, off
	v_or_b32_e32 v106, 8, v2
	v_max_i32_e32 v3, s30, v2
	v_min_i32_e32 v37, s31, v106
	v_sub_u32_e32 v3, v37, v3
	v_cvt_f32_i32_e32 v3, v3
	v_sub_f32_e32 v39, v157, v158
	v_sub_f32_e32 v105, v154, v162
	v_ashrrev_i32_e32 v107, 31, v106
	v_rcp_iflag_f32_e32 v3, v3
	s_nop 0
	v_fma_f32 v3, v3, v105, -v39
	v_cvt_pk_bf16_f32 v3, v3, s0
	global_store_short v[108:109], v3, off
	v_or_b32_e32 v108, 9, v2
	v_max_i32_e32 v3, s30, v110
	v_min_i32_e32 v37, s31, v108
	v_sub_u32_e32 v3, v37, v3
	v_cvt_f32_i32_e32 v3, v3
	v_sub_f32_e32 v39, v156, v157
	v_sub_f32_e32 v105, v153, v161
	v_ashrrev_i32_e32 v37, 31, v36
	v_rcp_iflag_f32_e32 v3, v3
	v_lshlrev_b64 v[110:111], 11, v[36:37]
	v_lshl_add_u64 v[110:111], v[44:45], 0, v[110:111]
	v_ashrrev_i32_e32 v109, 31, v108
	v_fma_f32 v3, v3, v105, -v39
	v_cvt_pk_bf16_f32 v3, v3, s0
	global_store_short v[110:111], v3, off
	v_or_b32_e32 v110, 10, v2
	v_max_i32_e32 v3, s30, v114
	v_min_i32_e32 v37, s31, v110
	v_sub_u32_e32 v3, v37, v3
	v_cvt_f32_i32_e32 v3, v3
	v_sub_f32_e32 v39, v155, v156
	v_sub_f32_e32 v105, v1, v160
	v_ashrrev_i32_e32 v111, 31, v110
	v_rcp_iflag_f32_e32 v3, v3
	s_nop 0
	v_fma_f32 v3, v3, v105, -v39
	v_ashrrev_i32_e32 v39, 31, v38
	v_lshlrev_b64 v[114:115], 11, v[38:39]
	v_cvt_pk_bf16_f32 v3, v3, s0
	v_lshl_add_u64 v[114:115], v[44:45], 0, v[114:115]
	global_store_short v[114:115], v3, off
	v_or_b32_e32 v114, 11, v2
	v_max_i32_e32 v3, s30, v116
	v_min_i32_e32 v37, s31, v114
	v_sub_u32_e32 v3, v37, v3
	v_cvt_f32_i32_e32 v3, v3
	v_sub_f32_e32 v39, v154, v155
	v_sub_f32_e32 v105, v169, v159
	v_ashrrev_i32_e32 v115, 31, v114
	v_rcp_iflag_f32_e32 v3, v3
	s_nop 0
	v_fma_f32 v3, v3, v105, -v39
	v_ashrrev_i32_e32 v105, 31, v104
	v_lshlrev_b64 v[116:117], 11, v[104:105]
	v_cvt_pk_bf16_f32 v3, v3, s0
	v_lshl_add_u64 v[116:117], v[44:45], 0, v[116:117]
	global_store_short v[116:117], v3, off
	v_or_b32_e32 v116, 12, v2
	v_max_i32_e32 v3, s30, v112
	v_min_i32_e32 v37, s31, v116
	v_sub_u32_e32 v3, v37, v3
	v_cvt_f32_i32_e32 v3, v3
	v_sub_f32_e32 v39, v153, v154
	v_sub_f32_e32 v105, v168, v158
	v_lshlrev_b64 v[112:113], 11, v[106:107]
	v_rcp_iflag_f32_e32 v3, v3
	v_lshl_add_u64 v[112:113], v[44:45], 0, v[112:113]
	v_sub_f32_e32 v37, v1, v153
	v_ashrrev_i32_e32 v117, 31, v116
	v_fma_f32 v3, v3, v105, -v39
	v_cvt_pk_bf16_f32 v3, v3, s0
	global_store_short v[112:113], v3, off
	v_max_i32_e32 v3, s30, v36
	v_min_i32_e32 v36, s31, v118
	v_sub_u32_e32 v3, v36, v3
	v_cvt_f32_i32_e32 v3, v3
	v_sub_f32_e32 v39, v166, v157
	v_or_b32_e32 v112, 14, v2
	v_ashrrev_i32_e32 v113, 31, v112
	v_rcp_iflag_f32_e32 v3, v3
	s_nop 0
	v_fma_f32 v3, v3, v39, -v37
	v_lshlrev_b64 v[36:37], 11, v[108:109]
	v_cvt_pk_bf16_f32 v3, v3, s0
	v_lshl_add_u64 v[36:37], v[44:45], 0, v[36:37]
	global_store_short v[36:37], v3, off
	v_max_i32_e32 v3, s30, v38
	v_min_i32_e32 v36, s31, v112
	v_sub_u32_e32 v3, v36, v3
	v_cvt_f32_i32_e32 v3, v3
	v_sub_f32_e32 v37, v169, v1
	v_sub_f32_e32 v38, v167, v156
	v_sub_f32_e32 v39, v165, v155
	v_rcp_iflag_f32_e32 v3, v3
	s_nop 0
	v_fma_f32 v3, v3, v38, -v37
	v_lshlrev_b64 v[36:37], 11, v[110:111]
	v_cvt_pk_bf16_f32 v3, v3, s0
	v_lshl_add_u64 v[36:37], v[44:45], 0, v[36:37]
	global_store_short v[36:37], v3, off
	v_or_b32_e32 v36, 15, v2
	v_max_i32_e32 v3, s30, v104
	v_min_i32_e32 v37, s31, v36
	v_sub_u32_e32 v3, v37, v3
	v_cvt_f32_i32_e32 v3, v3
	v_sub_f32_e32 v38, v168, v169
	v_max_i32_e32 v37, s30, v106
	v_rcp_iflag_f32_e32 v3, v3
	s_nop 0
	v_fma_f32 v3, v3, v39, -v38
	v_lshlrev_b64 v[38:39], 11, v[114:115]
	v_cvt_pk_bf16_f32 v3, v3, s0
	v_lshl_add_u64 v[38:39], v[44:45], 0, v[38:39]
	global_store_short v[38:39], v3, off
	v_add_u32_e32 v3, 16, v2
	v_min_i32_e32 v3, s31, v3
	v_sub_u32_e32 v3, v3, v37
	v_cvt_f32_i32_e32 v3, v3
	v_sub_f32_e32 v38, v166, v168
	v_sub_f32_e32 v39, v170, v154
	v_max_i32_e32 v37, s30, v108
	v_rcp_iflag_f32_e32 v3, v3
	s_nop 0
	v_fma_f32 v3, v3, v39, -v38
	v_lshlrev_b64 v[38:39], 11, v[116:117]
	v_cvt_pk_bf16_f32 v3, v3, s0
	v_lshl_add_u64 v[38:39], v[44:45], 0, v[38:39]
	global_store_short v[38:39], v3, off
	v_add_u32_e32 v3, 17, v2
	v_min_i32_e32 v3, s31, v3
	v_sub_u32_e32 v3, v3, v37
	v_cvt_f32_i32_e32 v3, v3
	v_sub_f32_e32 v38, v167, v166
	v_sub_f32_e32 v39, v171, v153
	v_max_i32_e32 v37, s30, v110
	v_rcp_iflag_f32_e32 v3, v3
	s_nop 0
	v_fma_f32 v3, v3, v39, -v38
	v_lshlrev_b64 v[38:39], 11, v[118:119]
	v_cvt_pk_bf16_f32 v3, v3, s0
	v_lshl_add_u64 v[38:39], v[44:45], 0, v[38:39]
	global_store_short v[38:39], v3, off
	v_add_u32_e32 v3, 18, v2
	v_min_i32_e32 v3, s31, v3
	v_sub_u32_e32 v3, v3, v37
	v_cvt_f32_i32_e32 v3, v3
	v_sub_f32_e32 v38, v165, v167
	v_sub_f32_e32 v39, v175, v1
	v_max_i32_e32 v37, s30, v114
	v_rcp_iflag_f32_e32 v3, v3
	s_nop 0
	v_fma_f32 v3, v3, v39, -v38
	v_lshlrev_b64 v[38:39], 11, v[112:113]
	v_cvt_pk_bf16_f32 v3, v3, s0
	v_lshl_add_u64 v[38:39], v[44:45], 0, v[38:39]
	global_store_short v[38:39], v3, off
	v_add_u32_e32 v3, 19, v2
	v_min_i32_e32 v38, s31, v3
	v_sub_f32_e32 v3, v174, v169
	v_sub_u32_e32 v38, v38, v37
